# lever 2 store de-serialisation: head-norm partial sums (SS) re-laid out [chunk][head][slice][token] so each scan output wave stores one full 128-B line per step instead of 16 partial lines; table buil
# baseline (speedup 1.0000x reference)
.LBB0_266:
	s_and_b64 vcc, exec, s[16:17]
	s_cbranch_vccz .LBB0_210
	s_bfe_u32 s16, s92, 0x40003
	s_lshl_b32 s17, s0, 9
	s_lshl_b32 s22, s16, 5
	s_or_b32 s17, s17, s22
	v_lshl_or_b32 v2, s0, 8, v201
	s_lshl_b32 s95, s16, 1
	s_lshl_b32 s16, s25, 13
	s_add_i32 s86, s17, 0x800
	v_mad_u32_u24 v2, v1, s66, v2
	v_or_b32_e32 v1, s93, v190
	s_lshl_b32 s93, s0, 5
	s_ashr_i32 s17, s16, 31
	s_waitcnt vmcnt(12)
	v_mul_u32_u24_e32 v4, 0x3040, v1
	s_mul_hi_i32 s23, s16, 0x6080
	s_add_u32 s22, s56, s61
	v_add3_u32 v166, v210, s86, v4
	s_addc_u32 s23, s57, s23
	v_lshlrev_b64 v[4:5], 1, v[2:3]
	s_waitcnt vmcnt(0)
	v_lshl_add_u64 v[6:7], s[22:23], 0, v[4:5]
	v_add_co_u32_e32 v8, vcc, s81, v6
	s_lshl_b32 s26, s25, 9
	s_nop 0
	v_addc_co_u32_e32 v9, vcc, 0, v7, vcc
	global_load_dwordx4 v[64:67], v[6:7], off
	global_load_dwordx4 v[56:59], v[8:9], off offset:256
	v_add_co_u32_e32 v8, vcc, s82, v6
	s_add_i32 s26, s26, s0
	s_nop 0
	v_addc_co_u32_e32 v9, vcc, 0, v7, vcc
	v_add_co_u32_e32 v10, vcc, s83, v6
	s_ashr_i32 s27, s26, 31
	s_nop 0
	v_addc_co_u32_e32 v11, vcc, 0, v7, vcc
	global_load_dwordx4 v[68:71], v[8:9], off offset:512
	global_load_dwordx4 v[60:63], v[10:11], off offset:768
	v_add_co_u32_e32 v8, vcc, s84, v6
	s_lshl_b64 s[74:75], s[26:27], 13
	s_nop 0
	v_addc_co_u32_e32 v9, vcc, 0, v7, vcc
	v_add_u32_e32 v168, s86, v211
	v_mov_b32_e32 v169, v3
	v_mov_b32_e32 v167, v3
	v_add_co_u32_e32 v10, vcc, s85, v6
	s_add_u32 s74, s58, s74
	v_lshlrev_b64 v[44:45], 1, v[168:169]
	v_lshlrev_b64 v[102:103], 1, v[166:167]
	v_addc_co_u32_e32 v11, vcc, 0, v7, vcc
	s_addc_u32 s75, s59, s75
	v_lshl_add_u64 v[20:21], s[22:23], 0, v[44:45]
	v_lshl_add_u64 v[22:23], s[22:23], 0, v[102:103]
	s_or_b32 s22, s16, 64
	global_load_dwordx4 v[80:83], v[8:9], off offset:1024
	global_load_dwordx4 v[72:75], v[10:11], off offset:1280
	v_add_co_u32_e32 v8, vcc, s89, v6
	s_lshl_b32 s60, s60, 11
	s_mul_hi_i32 s23, s22, 0x6080
	s_mulk_i32 s22, 0x6080
	v_addc_co_u32_e32 v9, vcc, 0, v7, vcc
	s_add_u32 s22, s56, s22
	v_add_co_u32_e32 v6, vcc, s90, v6
	s_addc_u32 s23, s57, s23
	s_nop 0
	v_addc_co_u32_e32 v7, vcc, 0, v7, vcc
	v_lshl_add_u64 v[28:29], s[22:23], 0, v[4:5]
	global_load_dwordx4 v[88:91], v[8:9], off offset:1536
	global_load_dwordx4 v[84:87], v[6:7], off offset:1792
	v_add_co_u32_e32 v8, vcc, s81, v28
	s_add_i32 s26, s26, 4
	s_nop 0
	v_addc_co_u32_e32 v9, vcc, 0, v29, vcc
	v_add_co_u32_e32 v12, vcc, s82, v28
	v_lshl_or_b32 v100, v196, 1, s60
	s_nop 0
	v_addc_co_u32_e32 v13, vcc, 0, v29, vcc
	v_add_co_u32_e32 v16, vcc, s83, v28
	s_ashr_i32 s27, s26, 31
	s_nop 0
	v_addc_co_u32_e32 v17, vcc, 0, v29, vcc
	v_add_co_u32_e32 v24, vcc, s84, v28
	global_load_dwordx4 v[92:95], v100, s[74:75]
	global_load_dwordx4 v[76:79], v100, s[74:75] offset:1024
	v_addc_co_u32_e32 v25, vcc, 0, v29, vcc
	v_add_co_u32_e32 v26, vcc, s85, v28
	s_lshl_b64 s[26:27], s[26:27], 13
	s_nop 0
	v_addc_co_u32_e32 v27, vcc, 0, v29, vcc
	v_add_co_u32_e32 v30, vcc, s89, v28
	global_load_dwordx4 v[4:7], v[28:29], off
	s_nop 0
	global_load_dwordx4 v[8:11], v[8:9], off offset:256
	s_nop 0
	global_load_dwordx4 v[12:15], v[12:13], off offset:512
	s_nop 0
	global_load_dwordx4 v[16:19], v[16:17], off offset:768
	s_nop 0
	global_load_dwordx4 v[52:55], v[22:23], off
	global_load_dwordx4 v[96:99], v[20:21], off
	v_addc_co_u32_e32 v31, vcc, 0, v29, vcc
	v_add_co_u32_e32 v32, vcc, s90, v28
	s_add_u32 s26, s58, s26
	s_nop 0
	v_addc_co_u32_e32 v33, vcc, 0, v29, vcc
	s_addc_u32 s27, s59, s27
	v_lshl_add_u64 v[44:45], s[22:23], 0, v[44:45]
	v_lshl_add_u64 v[48:49], s[22:23], 0, v[102:103]
	global_load_dwordx4 v[20:23], v[24:25], off offset:1024
	s_nop 0
	global_load_dwordx4 v[24:27], v[26:27], off offset:1280
	s_nop 0
	global_load_dwordx4 v[28:31], v[30:31], off offset:1536
	s_nop 0
	global_load_dwordx4 v[32:35], v[32:33], off offset:1792
	s_nop 0
	global_load_dwordx4 v[36:39], v100, s[26:27]
	global_load_dwordx4 v[40:43], v100, s[26:27] offset:1024
	s_nop 0
	global_load_dwordx4 v[44:47], v[44:45], off
	s_nop 0
	global_load_dwordx4 v[48:51], v[48:49], off
	s_lshl_b64 s[22:23], s[16:17], 9
	s_lshl_b32 s17, s24, 5
	s_or_b32 s17, s95, s17
	v_lshl_add_u32 v1, v1, 7, s93
	s_add_i32 s17, s17, s60
	v_or_b32_e32 v104, s95, v1
	s_lshl_b32 s93, s25, 7
	v_add_u32_e32 v1, s17, v226
	s_waitcnt vmcnt(8)
	ds_write_b16 v212, v96 offset:33792
	ds_write_b16_d16_hi v212, v96 offset:33936
	ds_write_b16 v212, v97 offset:34080
	ds_write_b16_d16_hi v212, v97 offset:34224
	ds_write_b16 v212, v98 offset:36096
	ds_write_b16_d16_hi v212, v98 offset:36240
	ds_write_b16 v212, v99 offset:36384
	ds_write_b16_d16_hi v212, v99 offset:36528
	v_subrev_u32_e32 v96, s93, v1
	v_mov_b32_e32 v97, v3
	v_mov_b32_e32 v101, v3
	v_mov_b32_e32 v105, v3
	v_lshl_add_u64 v[176:177], v[96:97], 2, s[22:23]
	v_mad_i64_i32 v[178:179], s[22:23], s16, v230, v[102:103]
	s_mov_b32 s94, 0
	v_lshl_add_u64 v[170:171], s[56:57], 0, v[102:103]
	v_lshl_add_u64 v[172:173], s[58:59], 0, v[100:101]
	v_lshl_add_u64 v[174:175], v[104:105], 2, s[54:55]
	s_or_b32 s22, s16, 0x80
	v_lshrrev_b32_e32 v220, 6, v151
	v_and_b32_e32 v221, 15, v151
	v_lshl_add_u32 v220, v220, 4, v221
	s_lshr_b32 s98, s92, 3
	s_and_b32 s98, s98, 15
	s_mul_i32 s99, s0, 0x7e0
	s_mul_i32 s98, s98, 0x7e
	s_add_i32 s99, s99, s98
	v_mul_i32_i24_e32 v220, 0xffffff82, v220
	v_add_u32_e32 v220, s99, v220
	v_ashrrev_i32_e32 v221, 31, v220
	v_lshl_add_u64 v[176:177], v[220:221], 2, v[176:177]
	v_lshl_add_u64 v[174:175], v[220:221], 2, v[174:175]
	s_branch .LBB0_270

.LBB0_383:
	v_ashrrev_i32_e32 v3, 31, v2
	v_lshrrev_b32_e32 v3, 30, v3
	v_add_u32_e32 v3, v2, v3
	v_ashrrev_i32_e32 v36, 2, v3
	v_and_b32_e32 v3, -4, v3
	s_waitcnt vmcnt(0)
	v_add_u32_e32 v6, s6, v36
	v_sub_u32_e32 v4, v2, v3
	v_lshrrev_b32_e32 v7, 6, v6
	v_lshl_add_u32 v7, v7, 2, v4
	v_and_b32_e32 v5, 63, v6
	v_lshlrev_b32_e32 v7, 13, v7
	v_lshl_add_u32 v38, v5, 3, v7
	v_add_u32_e32 v39, 0x1000, v38
	global_load_dwordx2 v[4:5], v38, s[54:55]
	global_load_dwordx2 v[6:7], v38, s[54:55] offset:512
	global_load_dwordx2 v[8:9], v38, s[54:55] offset:1024
	global_load_dwordx2 v[10:11], v38, s[54:55] offset:1536
	global_load_dwordx2 v[12:13], v38, s[54:55] offset:2048
	global_load_dwordx2 v[14:15], v38, s[54:55] offset:2560
	global_load_dwordx2 v[16:17], v38, s[54:55] offset:3072
	global_load_dwordx2 v[18:19], v38, s[54:55] offset:3584
	global_load_dwordx2 v[20:21], v39, s[54:55]
	global_load_dwordx2 v[22:23], v39, s[54:55] offset:512
	global_load_dwordx2 v[24:25], v39, s[54:55] offset:1024
	global_load_dwordx2 v[26:27], v39, s[54:55] offset:1536
	global_load_dwordx2 v[28:29], v39, s[54:55] offset:2048
	global_load_dwordx2 v[30:31], v39, s[54:55] offset:2560
	global_load_dwordx2 v[32:33], v39, s[54:55] offset:3072
	global_load_dwordx2 v[34:35], v39, s[54:55] offset:3584
	v_add_u32_e32 v37, 0x200, v2
	v_cmp_lt_i32_e32 vcc, s9, v2
	s_or_b64 s[4:5], vcc, s[4:5]
	s_waitcnt vmcnt(0)
	v_mov_b32_e32 v2, v4
	s_waitcnt vmcnt(6)
	v_mov_b32_e32 v3, v8
	v_mov_b32_e32 v8, v5
	v_mov_b32_e32 v4, v6
	v_mov_b32_e32 v5, v10
	v_mov_b32_e32 v10, v7
	s_waitcnt vmcnt(5)
	v_mov_b32_e32 v6, v13
	v_mov_b32_e32 v7, v14
	v_mov_b32_e32 v13, v15
	v_pk_add_f32 v[2:3], v[2:3], v[8:9]
	v_pk_add_f32 v[4:5], v[4:5], v[10:11]
	v_pk_add_f32 v[6:7], v[6:7], v[12:13]
	v_pk_add_f32 v[2:3], v[2:3], v[4:5]
	v_pk_add_f32 v[4:5], v[6:7], v[6:7] op_sel:[0,1] op_sel_hi:[1,0]
	v_add_f32_e32 v2, 0, v2
	s_waitcnt vmcnt(4)
	v_add_f32_e32 v14, v16, v17
	v_add_f32_e32 v16, v18, v19
	s_waitcnt vmcnt(3)
	v_mov_b32_e32 v19, v20
	v_mov_b32_e32 v15, v22
	v_mov_b32_e32 v17, v23
	v_mov_b32_e32 v5, v21
	v_add_f32_e32 v18, v2, v3
	s_waitcnt vmcnt(2)
	v_mov_b32_e32 v22, v25
	v_mov_b32_e32 v23, v26
	v_mov_b32_e32 v25, v27
	v_pk_add_f32 v[8:9], v[14:15], v[16:17]
	v_pk_add_f32 v[2:3], v[18:19], v[4:5]
	v_pk_add_f32 v[10:11], v[22:23], v[24:25]
	v_pk_add_f32 v[2:3], v[2:3], v[8:9]
	v_pk_add_f32 v[6:7], v[10:11], v[10:11] op_sel:[0,1] op_sel_hi:[1,0]
	v_pk_add_f32 v[2:3], v[2:3], v[2:3] op_sel:[0,1] op_sel_hi:[1,0]
	s_waitcnt vmcnt(1)
	v_add_f32_e32 v26, v28, v29
	v_add_f32_e32 v28, v30, v31
	s_waitcnt vmcnt(0)
	v_mov_b32_e32 v27, v34
	v_mov_b32_e32 v29, v35
	v_mov_b32_e32 v7, v33
	v_mov_b32_e32 v3, v32
	v_pk_add_f32 v[12:13], v[26:27], v[28:29]
	v_pk_add_f32 v[2:3], v[2:3], v[6:7]
	v_mad_u64_u32 v[4:5], s[10:11], v36, s8, v[0:1]
	v_pk_add_f32 v[2:3], v[2:3], v[12:13]
	v_add_u32_e32 v0, 0x80000, v0
	v_add_f32_e32 v2, v2, v3
	v_fmamk_f32 v2, v2, 0x3b000000, v1
	v_mul_f32_e32 v3, 0x4b800000, v2
	v_cmp_gt_f32_e32 vcc, s7, v2
	s_nop 1
	v_cndmask_b32_e32 v2, v2, v3, vcc
	v_rsq_f32_e32 v3, v2
	v_mov_b32_e32 v2, v37
	v_mul_f32_e32 v5, 0x45800000, v3
	v_cndmask_b32_e32 v3, v3, v5, vcc
	ds_write_b32 v4, v3
	s_andn2_b64 exec, exec, s[4:5]
	s_cbranch_execnz .LBB0_383

.LBB0_708:
	s_and_b64 vcc, exec, s[6:7]
	s_cbranch_vccz .LBB0_681
	s_bfe_u32 s6, s27, 0x40003
	s_lshl_b32 s7, s35, 9
	s_lshl_b32 s10, s6, 5
	s_or_b32 s7, s7, s10
	s_lshl_b32 s43, s6, 1
	s_lshl_b32 s6, s13, 13
	s_add_i32 s11, s7, 0x1000
	v_lshl_or_b32 v0, s35, 8, v173
	s_lshl_b32 s42, s35, 5
	s_ashr_i32 s7, s6, 31
	v_mad_u32_u24 v0, v148, s16, v0
	s_waitcnt vmcnt(11)
	v_or_b32_e32 v99, s36, v171
	s_mul_hi_i32 s37, s6, 0x6080
	s_add_u32 s36, s56, s15
	s_addc_u32 s37, s57, s37
	v_lshlrev_b64 v[2:3], 1, v[0:1]
	s_waitcnt vmcnt(0)
	v_lshl_add_u64 v[4:5], s[36:37], 0, v[2:3]
	v_add_co_u32_e32 v6, vcc, s18, v4
	s_lshl_b32 s15, s13, 10
	s_nop 0
	v_addc_co_u32_e32 v7, vcc, 0, v5, vcc
	global_load_dwordx4 v[62:65], v[4:5], off
	global_load_dwordx4 v[54:57], v[6:7], off offset:256
	v_add_co_u32_e32 v6, vcc, s19, v4
	s_add_i32 s38, s15, s35
	s_nop 0
	v_addc_co_u32_e32 v7, vcc, 0, v5, vcc
	v_add_co_u32_e32 v8, vcc, s20, v4
	s_ashr_i32 s39, s38, 31
	s_nop 0
	v_addc_co_u32_e32 v9, vcc, 0, v5, vcc
	global_load_dwordx4 v[66:69], v[6:7], off offset:512
	global_load_dwordx4 v[58:61], v[8:9], off offset:768
	v_add_co_u32_e32 v6, vcc, s21, v4
	s_lshl_b64 s[40:41], s[38:39], 13
	s_nop 0
	v_addc_co_u32_e32 v7, vcc, 0, v5, vcc
	v_mul_u32_u24_e32 v104, 0x3040, v99
	v_add_co_u32_e32 v8, vcc, s22, v4
	s_add_u32 s40, s58, s40
	v_add3_u32 v148, v182, s11, v104
	v_addc_co_u32_e32 v9, vcc, 0, v5, vcc
	s_addc_u32 s41, s59, s41
	v_add_u32_e32 v150, s11, v183
	v_mov_b32_e32 v151, v1
	v_mov_b32_e32 v149, v1
	s_or_b32 s11, s6, 64
	global_load_dwordx4 v[78:81], v[6:7], off offset:1024
	global_load_dwordx4 v[70:73], v[8:9], off offset:1280
	v_add_co_u32_e32 v6, vcc, s23, v4
	v_lshlrev_b64 v[42:43], 1, v[150:151]
	v_lshlrev_b64 v[100:101], 1, v[148:149]
	s_mul_hi_i32 s15, s11, 0x6080
	s_mulk_i32 s11, 0x6080
	v_addc_co_u32_e32 v7, vcc, 0, v5, vcc
	v_lshl_add_u64 v[10:11], s[36:37], 0, v[42:43]
	v_lshl_add_u64 v[12:13], s[36:37], 0, v[100:101]
	s_add_u32 s36, s56, s11
	v_add_co_u32_e32 v4, vcc, s24, v4
	s_addc_u32 s37, s57, s15
	s_nop 0
	v_addc_co_u32_e32 v5, vcc, 0, v5, vcc
	v_lshl_add_u64 v[26:27], s[36:37], 0, v[2:3]
	global_load_dwordx4 v[86:89], v[6:7], off offset:1536
	global_load_dwordx4 v[82:85], v[4:5], off offset:1792
	v_add_co_u32_e32 v6, vcc, s18, v26
	v_lshl_or_b32 v98, s14, 11, v193
	s_nop 0
	v_addc_co_u32_e32 v7, vcc, 0, v27, vcc
	v_add_co_u32_e32 v14, vcc, s19, v26
	global_load_dwordx4 v[90:93], v98, s[40:41]
	global_load_dwordx4 v[74:77], v98, s[40:41] offset:1024
	v_addc_co_u32_e32 v15, vcc, 0, v27, vcc
	v_add_co_u32_e32 v16, vcc, s20, v26
	global_load_dwordx4 v[2:5], v[26:27], off
	s_nop 0
	global_load_dwordx4 v[6:9], v[6:7], off offset:256
	v_addc_co_u32_e32 v17, vcc, 0, v27, vcc
	global_load_dwordx4 v[50:53], v[12:13], off
	global_load_dwordx4 v[94:97], v[10:11], off
	v_add_co_u32_e32 v18, vcc, s21, v26
	s_add_i32 s38, s38, 8
	s_nop 0
	v_addc_co_u32_e32 v19, vcc, 0, v27, vcc
	v_add_co_u32_e32 v22, vcc, s22, v26
	s_ashr_i32 s39, s38, 31
	s_nop 0
	v_addc_co_u32_e32 v23, vcc, 0, v27, vcc
	v_add_co_u32_e32 v28, vcc, s23, v26
	s_lshl_b64 s[38:39], s[38:39], 13
	s_nop 0
	v_addc_co_u32_e32 v29, vcc, 0, v27, vcc
	v_add_co_u32_e32 v30, vcc, s24, v26
	s_add_u32 s38, s58, s38
	s_nop 0
	v_addc_co_u32_e32 v31, vcc, 0, v27, vcc
	s_addc_u32 s39, s59, s39
	v_lshl_add_u64 v[42:43], s[36:37], 0, v[42:43]
	v_lshl_add_u64 v[46:47], s[36:37], 0, v[100:101]
	global_load_dwordx4 v[10:13], v[14:15], off offset:512
	s_nop 0
	global_load_dwordx4 v[14:17], v[16:17], off offset:768
	s_nop 0
	global_load_dwordx4 v[18:21], v[18:19], off offset:1024
	s_nop 0
	global_load_dwordx4 v[22:25], v[22:23], off offset:1280
	s_nop 0
	global_load_dwordx4 v[26:29], v[28:29], off offset:1536
	s_nop 0
	global_load_dwordx4 v[30:33], v[30:31], off offset:1792
	s_nop 0
	global_load_dwordx4 v[34:37], v98, s[38:39]
	global_load_dwordx4 v[38:41], v98, s[38:39] offset:1024
	s_nop 0
	global_load_dwordx4 v[42:45], v[42:43], off
	s_nop 0
	global_load_dwordx4 v[46:49], v[46:47], off
	s_lshl_b32 s11, s12, 5
	s_lshl_b64 s[38:39], s[6:7], 10
	s_lshl_b32 s7, s14, 12
	s_or_b32 s11, s43, s11
	s_add_i32 s11, s11, s7
	s_waitcnt vmcnt(10)
	ds_write_b16 v184, v94 offset:33792
	ds_write_b16_d16_hi v184, v94 offset:33936
	ds_write_b16 v184, v95 offset:34080
	ds_write_b16_d16_hi v184, v95 offset:34224
	ds_write_b16 v184, v96 offset:36096
	ds_write_b16_d16_hi v184, v96 offset:36240
	ds_write_b16 v184, v97 offset:36384
	ds_write_b16_d16_hi v184, v97 offset:36528
	v_add_u32_e32 v94, s11, v191
	s_lshl_b32 s7, s13, 8
	v_subrev_u32_e32 v94, s7, v94
	s_lshl_b32 s7, s12, 9
	v_mov_b32_e32 v95, v1
	s_or_b32 s7, s10, s7
	v_lshl_add_u64 v[158:159], v[94:95], 2, s[38:39]
	v_add3_u32 v94, v192, v104, s7
	s_lshl_b32 s7, s13, 12
	v_subrev_u32_e32 v94, s7, v94
	v_lshl_add_u32 v99, v99, 8, s42
	v_lshlrev_b64 v[94:95], 1, v[94:95]
	v_or_b32_e32 v102, s43, v99
	v_mov_b32_e32 v99, v1
	v_mov_b32_e32 v103, v1
	v_mad_i64_i32 v[160:161], s[10:11], s6, v194, v[94:95]
	s_mov_b32 s37, 0
	s_lshl_b32 s36, s13, 7
	v_lshl_add_u64 v[152:153], s[56:57], 0, v[100:101]
	v_lshl_add_u64 v[154:155], s[58:59], 0, v[98:99]
	v_lshl_add_u64 v[156:157], v[102:103], 2, s[54:55]
	s_or_b32 s10, s6, 0x80
	v_lshrrev_b32_e32 v220, 6, v170
	v_and_b32_e32 v221, 15, v170
	v_lshl_add_u32 v220, v220, 4, v221
	s_bfe_u32 s98, s27, 0x40003
	s_mul_i32 s99, s35, 0x7e0
	s_mul_i32 s98, s98, 0x7e
	s_add_i32 s99, s99, s98
	v_mul_i32_i24_e32 v220, 0xffffff02, v220
	v_add_u32_e32 v220, s99, v220
	v_ashrrev_i32_e32 v221, 31, v220
	v_lshl_add_u64 v[158:159], v[220:221], 2, v[158:159]
	v_lshl_add_u64 v[156:157], v[220:221], 2, v[156:157]
	s_branch .LBB0_712

.LBB0_867:
	v_ashrrev_i32_e32 v3, 31, v2
	v_lshrrev_b32_e32 v3, 29, v3
	v_add_u32_e32 v3, v2, v3
	v_ashrrev_i32_e32 v38, 3, v3
	v_and_b32_e32 v3, -8, v3
	v_add_u32_e32 v6, s6, v38
	v_sub_u32_e32 v4, v2, v3
	v_lshrrev_b32_e32 v7, 6, v6
	v_lshl_add_u32 v7, v7, 3, v4
	v_and_b32_e32 v5, 63, v6
	v_lshlrev_b32_e32 v7, 13, v7
	v_lshl_add_u32 v36, v5, 3, v7
	v_add_u32_e32 v37, 0x1000, v36
	global_load_dwordx2 v[4:5], v36, s[54:55]
	global_load_dwordx2 v[6:7], v36, s[54:55] offset:512
	global_load_dwordx2 v[8:9], v36, s[54:55] offset:1024
	global_load_dwordx2 v[10:11], v36, s[54:55] offset:1536
	global_load_dwordx2 v[12:13], v36, s[54:55] offset:2048
	global_load_dwordx2 v[14:15], v36, s[54:55] offset:2560
	global_load_dwordx2 v[16:17], v36, s[54:55] offset:3072
	global_load_dwordx2 v[18:19], v36, s[54:55] offset:3584
	global_load_dwordx2 v[20:21], v37, s[54:55]
	global_load_dwordx2 v[22:23], v37, s[54:55] offset:512
	global_load_dwordx2 v[24:25], v37, s[54:55] offset:1024
	global_load_dwordx2 v[26:27], v37, s[54:55] offset:1536
	global_load_dwordx2 v[28:29], v37, s[54:55] offset:2048
	global_load_dwordx2 v[30:31], v37, s[54:55] offset:2560
	global_load_dwordx2 v[32:33], v37, s[54:55] offset:3072
	global_load_dwordx2 v[34:35], v37, s[54:55] offset:3584
	v_add_u32_e32 v36, 0x200, v2
	v_cmp_lt_i32_e32 vcc, s9, v2
	s_or_b64 s[4:5], vcc, s[4:5]
	s_waitcnt vmcnt(0)
	v_mov_b32_e32 v2, v4
	s_waitcnt vmcnt(6)
	v_mov_b32_e32 v3, v8
	v_mov_b32_e32 v8, v5
	v_mov_b32_e32 v4, v6
	v_mov_b32_e32 v5, v10
	v_mov_b32_e32 v10, v7
	s_waitcnt vmcnt(5)
	v_mov_b32_e32 v6, v13
	v_mov_b32_e32 v7, v14
	v_mov_b32_e32 v13, v15
	v_pk_add_f32 v[2:3], v[2:3], v[8:9]
	v_pk_add_f32 v[4:5], v[4:5], v[10:11]
	v_pk_add_f32 v[6:7], v[6:7], v[12:13]
	v_pk_add_f32 v[2:3], v[2:3], v[4:5]
	v_pk_add_f32 v[4:5], v[6:7], v[6:7] op_sel:[0,1] op_sel_hi:[1,0]
	v_add_f32_e32 v2, 0, v2
	s_waitcnt vmcnt(4)
	v_add_f32_e32 v14, v16, v17
	v_add_f32_e32 v16, v18, v19
	s_waitcnt vmcnt(3)
	v_mov_b32_e32 v19, v20
	v_mov_b32_e32 v15, v22
	v_mov_b32_e32 v17, v23
	v_mov_b32_e32 v5, v21
	v_add_f32_e32 v18, v2, v3
	s_waitcnt vmcnt(2)
	v_mov_b32_e32 v22, v25
	v_mov_b32_e32 v23, v26
	v_mov_b32_e32 v25, v27
	v_pk_add_f32 v[8:9], v[14:15], v[16:17]
	v_pk_add_f32 v[2:3], v[18:19], v[4:5]
	v_pk_add_f32 v[10:11], v[22:23], v[24:25]
	v_pk_add_f32 v[2:3], v[2:3], v[8:9]
	v_pk_add_f32 v[6:7], v[10:11], v[10:11] op_sel:[0,1] op_sel_hi:[1,0]
	v_pk_add_f32 v[2:3], v[2:3], v[2:3] op_sel:[0,1] op_sel_hi:[1,0]
	s_waitcnt vmcnt(1)
	v_add_f32_e32 v26, v28, v29
	v_add_f32_e32 v28, v30, v31
	s_waitcnt vmcnt(0)
	v_mov_b32_e32 v27, v34
	v_mov_b32_e32 v29, v35
	v_mov_b32_e32 v7, v33
	v_mov_b32_e32 v3, v32
	v_pk_add_f32 v[12:13], v[26:27], v[28:29]
	v_pk_add_f32 v[2:3], v[2:3], v[6:7]
	v_mad_u64_u32 v[4:5], s[10:11], v38, s8, v[0:1]
	v_pk_add_f32 v[2:3], v[2:3], v[12:13]
	v_add_u32_e32 v0, 0x80000, v0
	v_add_f32_e32 v2, v2, v3
	v_fmamk_f32 v2, v2, 0x3b000000, v1
	v_mul_f32_e32 v3, 0x4b800000, v2
	v_cmp_gt_f32_e32 vcc, s7, v2
	s_nop 1
	v_cndmask_b32_e32 v2, v2, v3, vcc
	v_rsq_f32_e32 v3, v2
	v_mov_b32_e32 v2, v36
	v_mul_f32_e32 v5, 0x45800000, v3
	v_cndmask_b32_e32 v3, v3, v5, vcc
	ds_write_b32 v4, v3
	s_andn2_b64 exec, exec, s[4:5]
	s_cbranch_execnz .LBB0_867
